# grid barrier: non-leader WGs poll TOPGEN directly, XGEN publish removed (on v18)
# speedup vs baseline: 1.0008x; 1.0008x over previous
.LBB0_134:
	s_or_b64 exec, exec, s[14:15]
	v_cvt_f32_u32_e32 v4, v2
	s_waitcnt vmcnt(0)
	v_readfirstlane_b32 s3, v3
	v_sub_u32_e32 v3, 0, v2
	v_rcp_iflag_f32_e32 v4, v4
	v_add_u32_e32 v5, s3, v1
	v_mul_f32_e32 v4, 0x4f7ffffe, v4
	v_cvt_u32_f32_e32 v4, v4
	v_mul_lo_u32 v1, v3, v4
	v_mul_hi_u32 v1, v4, v1
	v_add_u32_e32 v1, v4, v1
	v_mul_hi_u32 v1, v5, v1
	v_mul_lo_u32 v3, v1, v2
	v_sub_u32_e32 v3, v5, v3
	v_add_u32_e32 v4, 1, v1
	v_cmp_ge_u32_e32 vcc, v3, v2
	s_nop 1
	v_cndmask_b32_e32 v1, v1, v4, vcc
	v_sub_u32_e32 v4, v3, v2
	v_cndmask_b32_e32 v3, v3, v4, vcc
	v_add_u32_e32 v4, 1, v1
	v_cmp_ge_u32_e32 vcc, v3, v2
	v_add_u32_e32 v3, 1, v5
	s_nop 0
	v_cndmask_b32_e32 v1, v1, v4, vcc
	v_mul_lo_u32 v4, v2, v1
	v_add_u32_e32 v2, v4, v2
	v_cmp_ne_u32_e32 vcc, v3, v2
	s_and_saveexec_b64 s[12:13], vcc
	s_xor_b64 s[12:13], exec, s[12:13]
	s_cbranch_execz .LBB0_148
	s_waitcnt lgkmcnt(0)
	v_mov_b32_e32 v0, 0xe003500
	global_load_dword v0, v0, s[8:9] sc1
	s_add_u32 s18, s8, 0xe003500
	s_addc_u32 s19, s9, 0
	s_waitcnt vmcnt(0)
	v_cmp_eq_u32_e32 vcc, v0, v1
	s_and_saveexec_b64 s[14:15], vcc
	s_cbranch_execz .LBB0_147
	s_add_u32 s16, s8, 0xe000200
	s_addc_u32 s17, s9, 0
	s_mov_b32 s3, 1
	s_mov_b64 s[20:21], 0
	v_mov_b32_e32 v0, 0
	s_branch .LBB0_138

.LBB0_165:
	s_or_b64 exec, exec, s[8:9]
	s_mov_b64 s[8:9], exec
	v_mbcnt_lo_u32_b32 v0, s8, 0
	v_mbcnt_hi_u32_b32 v0, s9, v0
	v_cmp_eq_u32_e32 vcc, 0, v0
	s_waitcnt vmcnt(0)
	buffer_inv sc1
	s_and_saveexec_b64 s[12:13], vcc
	s_cbranch_execz .LBB0_167
	s_bcnt1_i32_b64 s3, s[8:9]
	v_mov_b32_e32 v0, 0x2000
	v_mov_b32_e32 v1, s3
.LBB0_167:
	s_or_b64 exec, exec, s[12:13]
	s_waitcnt vmcnt(0)

.LBB0_437:
	s_or_b64 exec, exec, s[16:17]
	v_cvt_f32_u32_e32 v4, v2
	s_waitcnt vmcnt(0)
	v_readfirstlane_b32 s14, v3
	v_sub_u32_e32 v3, 0, v2
	v_rcp_iflag_f32_e32 v4, v4
	v_add_u32_e32 v5, s14, v1
	v_mul_f32_e32 v4, 0x4f7ffffe, v4
	v_cvt_u32_f32_e32 v4, v4
	v_mul_lo_u32 v1, v3, v4
	v_mul_hi_u32 v1, v4, v1
	v_add_u32_e32 v1, v4, v1
	v_mul_hi_u32 v1, v5, v1
	v_mul_lo_u32 v3, v1, v2
	v_sub_u32_e32 v3, v5, v3
	v_add_u32_e32 v4, 1, v1
	v_cmp_ge_u32_e32 vcc, v3, v2
	s_nop 1
	v_cndmask_b32_e32 v1, v1, v4, vcc
	v_sub_u32_e32 v4, v3, v2
	v_cndmask_b32_e32 v3, v3, v4, vcc
	v_add_u32_e32 v4, 1, v1
	v_cmp_ge_u32_e32 vcc, v3, v2
	v_add_u32_e32 v3, 1, v5
	s_nop 0
	v_cndmask_b32_e32 v1, v1, v4, vcc
	v_mul_lo_u32 v4, v2, v1
	v_add_u32_e32 v2, v4, v2
	v_cmp_ne_u32_e32 vcc, v3, v2
	s_and_saveexec_b64 s[14:15], vcc
	s_xor_b64 s[14:15], exec, s[14:15]
	s_cbranch_execz .LBB0_451
	s_waitcnt lgkmcnt(0)
	v_mov_b32_e32 v0, 0xe003500
	global_load_dword v0, v0, s[10:11] sc1
	s_add_u32 s22, s10, 0xe003500
	s_addc_u32 s23, s11, 0
	s_waitcnt vmcnt(0)
	v_cmp_eq_u32_e32 vcc, v0, v1
	s_and_saveexec_b64 s[16:17], vcc
	s_cbranch_execz .LBB0_450
	s_add_u32 s18, s10, 0xe000200
	s_addc_u32 s19, s11, 0
	s_mov_b32 s26, 1
	s_mov_b64 s[34:35], 0
	v_mov_b32_e32 v0, 0
	s_branch .LBB0_441

.LBB0_468:
	s_or_b64 exec, exec, s[10:11]
	s_mov_b64 s[10:11], exec
	v_mbcnt_lo_u32_b32 v0, s10, 0
	v_mbcnt_hi_u32_b32 v0, s11, v0
	v_cmp_eq_u32_e32 vcc, 0, v0
	s_waitcnt vmcnt(0)
	buffer_inv sc1
	s_and_saveexec_b64 s[14:15], vcc
	s_cbranch_execz .LBB0_470
	s_bcnt1_i32_b64 s10, s[10:11]
	v_mov_b32_e32 v0, 0x2000
	v_mov_b32_e32 v1, s10
.LBB0_470:
	s_or_b64 exec, exec, s[14:15]
	s_waitcnt vmcnt(0)

.LBB0_592:
	s_or_b64 exec, exec, s[16:17]
	v_cvt_f32_u32_e32 v4, v2
	s_waitcnt vmcnt(0)
	v_readfirstlane_b32 s14, v3
	v_sub_u32_e32 v3, 0, v2
	v_rcp_iflag_f32_e32 v4, v4
	v_add_u32_e32 v5, s14, v1
	v_mul_f32_e32 v4, 0x4f7ffffe, v4
	v_cvt_u32_f32_e32 v4, v4
	v_mul_lo_u32 v1, v3, v4
	v_mul_hi_u32 v1, v4, v1
	v_add_u32_e32 v1, v4, v1
	v_mul_hi_u32 v1, v5, v1
	v_mul_lo_u32 v3, v1, v2
	v_sub_u32_e32 v3, v5, v3
	v_add_u32_e32 v4, 1, v1
	v_cmp_ge_u32_e32 vcc, v3, v2
	s_nop 1
	v_cndmask_b32_e32 v1, v1, v4, vcc
	v_sub_u32_e32 v4, v3, v2
	v_cndmask_b32_e32 v3, v3, v4, vcc
	v_add_u32_e32 v4, 1, v1
	v_cmp_ge_u32_e32 vcc, v3, v2
	v_add_u32_e32 v3, 1, v5
	s_nop 0
	v_cndmask_b32_e32 v1, v1, v4, vcc
	v_mul_lo_u32 v4, v2, v1
	v_add_u32_e32 v2, v4, v2
	v_cmp_ne_u32_e32 vcc, v3, v2
	s_and_saveexec_b64 s[14:15], vcc
	s_xor_b64 s[14:15], exec, s[14:15]
	s_cbranch_execz .LBB0_606
	s_waitcnt lgkmcnt(0)
	v_mov_b32_e32 v0, 0xe003500
	global_load_dword v0, v0, s[10:11] sc1
	s_add_u32 s34, s10, 0xe003500
	s_addc_u32 s35, s11, 0
	s_waitcnt vmcnt(0)
	v_cmp_eq_u32_e32 vcc, v0, v1
	s_and_saveexec_b64 s[16:17], vcc
	s_cbranch_execz .LBB0_605
	s_add_u32 s18, s10, 0xe000200
	s_addc_u32 s19, s11, 0
	s_mov_b32 s26, 1
	s_mov_b64 s[36:37], 0
	v_mov_b32_e32 v0, 0
	s_branch .LBB0_596

.LBB0_623:
	s_or_b64 exec, exec, s[10:11]
	s_mov_b64 s[10:11], exec
	v_mbcnt_lo_u32_b32 v0, s10, 0
	v_mbcnt_hi_u32_b32 v0, s11, v0
	v_cmp_eq_u32_e32 vcc, 0, v0
	s_waitcnt vmcnt(0)
	buffer_inv sc1
	s_and_saveexec_b64 s[14:15], vcc
	s_cbranch_execz .LBB0_625
	s_bcnt1_i32_b64 s10, s[10:11]
	v_mov_b32_e32 v0, 0x2000
	v_mov_b32_e32 v1, s10
.LBB0_625:
	s_or_b64 exec, exec, s[14:15]
	s_waitcnt vmcnt(0)

.LBB0_714:
	s_or_b64 exec, exec, s[10:11]
	s_mov_b64 s[10:11], exec
	v_mbcnt_lo_u32_b32 v0, s10, 0
	v_mbcnt_hi_u32_b32 v0, s11, v0
	v_cmp_eq_u32_e32 vcc, 0, v0
	s_waitcnt vmcnt(0)
	buffer_inv sc1
	s_and_saveexec_b64 s[14:15], vcc
	s_cbranch_execz .LBB0_716
	s_bcnt1_i32_b64 s10, s[10:11]
	v_mov_b32_e32 v0, 0x2000
	v_mov_b32_e32 v1, s10
.LBB0_716:
	s_or_b64 exec, exec, s[14:15]
	s_waitcnt vmcnt(0)

.LBB0_805:
	s_or_b64 exec, exec, s[10:11]
	s_mov_b64 s[10:11], exec
	v_mbcnt_lo_u32_b32 v0, s10, 0
	v_mbcnt_hi_u32_b32 v0, s11, v0
	v_cmp_eq_u32_e32 vcc, 0, v0
	s_waitcnt vmcnt(0)
	buffer_inv sc1
	s_and_saveexec_b64 s[14:15], vcc
	s_cbranch_execz .LBB0_807
	s_bcnt1_i32_b64 s10, s[10:11]
	v_mov_b32_e32 v0, 0x2000
	v_mov_b32_e32 v1, s10
.LBB0_807:
	s_or_b64 exec, exec, s[14:15]
	s_waitcnt vmcnt(0)

.LBB0_1006:
	s_or_b64 exec, exec, s[18:19]
	v_cvt_f32_u32_e32 v4, v2
	s_waitcnt vmcnt(0)
	v_readfirstlane_b32 s16, v3
	v_sub_u32_e32 v3, 0, v2
	v_rcp_iflag_f32_e32 v4, v4
	v_add_u32_e32 v5, s16, v1
	v_mul_f32_e32 v4, 0x4f7ffffe, v4
	v_cvt_u32_f32_e32 v4, v4
	v_mul_lo_u32 v1, v3, v4
	v_mul_hi_u32 v1, v4, v1
	v_add_u32_e32 v1, v4, v1
	v_mul_hi_u32 v1, v5, v1
	v_mul_lo_u32 v3, v1, v2
	v_sub_u32_e32 v3, v5, v3
	v_add_u32_e32 v4, 1, v1
	v_cmp_ge_u32_e32 vcc, v3, v2
	s_nop 1
	v_cndmask_b32_e32 v1, v1, v4, vcc
	v_sub_u32_e32 v4, v3, v2
	v_cndmask_b32_e32 v3, v3, v4, vcc
	v_add_u32_e32 v4, 1, v1
	v_cmp_ge_u32_e32 vcc, v3, v2
	v_add_u32_e32 v3, 1, v5
	s_nop 0
	v_cndmask_b32_e32 v1, v1, v4, vcc
	v_mul_lo_u32 v4, v2, v1
	v_add_u32_e32 v2, v4, v2
	v_cmp_ne_u32_e32 vcc, v3, v2
	s_and_saveexec_b64 s[16:17], vcc
	s_xor_b64 s[16:17], exec, s[16:17]
	s_cbranch_execz .LBB0_1020
	s_waitcnt lgkmcnt(0)
	v_mov_b32_e32 v0, 0xe003500
	global_load_dword v0, v0, s[12:13] sc1
	s_add_u32 s38, s12, 0xe003500
	s_addc_u32 s39, s13, 0
	s_waitcnt vmcnt(0)
	v_cmp_eq_u32_e32 vcc, v0, v1
	s_and_saveexec_b64 s[18:19], vcc
	s_cbranch_execz .LBB0_1019
	s_add_u32 s36, s12, 0xe000200
	s_addc_u32 s37, s13, 0
	s_mov_b32 s26, 1
	s_mov_b64 s[40:41], 0
	v_mov_b32_e32 v0, 0
	s_branch .LBB0_1010

.LBB0_1037:
	s_or_b64 exec, exec, s[12:13]
	s_mov_b64 s[12:13], exec
	v_mbcnt_lo_u32_b32 v0, s12, 0
	v_mbcnt_hi_u32_b32 v0, s13, v0
	v_cmp_eq_u32_e32 vcc, 0, v0
	s_waitcnt vmcnt(0)
	buffer_inv sc1
	s_and_saveexec_b64 s[16:17], vcc
	s_cbranch_execz .LBB0_1039
	s_bcnt1_i32_b64 s12, s[12:13]
	v_mov_b32_e32 v0, 0x2000
	v_mov_b32_e32 v1, s12
.LBB0_1039:
	s_or_b64 exec, exec, s[16:17]
	s_waitcnt vmcnt(0)

.LBB0_1131:
	s_or_b64 exec, exec, s[12:13]
	s_mov_b64 s[12:13], exec
	v_mbcnt_lo_u32_b32 v0, s12, 0
	v_mbcnt_hi_u32_b32 v0, s13, v0
	v_cmp_eq_u32_e32 vcc, 0, v0
	s_waitcnt vmcnt(0)
	buffer_inv sc1
	s_and_saveexec_b64 s[16:17], vcc
	s_cbranch_execz .LBB0_1133
	s_bcnt1_i32_b64 s12, s[12:13]
	v_mov_b32_e32 v0, 0x2000
	v_mov_b32_e32 v1, s12
.LBB0_1133:
	s_or_b64 exec, exec, s[16:17]
	s_waitcnt vmcnt(0)

.LBB0_1307:
	s_or_b64 exec, exec, s[18:19]
	v_cvt_f32_u32_e32 v4, v2
	s_waitcnt vmcnt(0)
	v_readfirstlane_b32 s16, v3
	v_sub_u32_e32 v3, 0, v2
	v_rcp_iflag_f32_e32 v4, v4
	v_add_u32_e32 v5, s16, v1
	v_mul_f32_e32 v4, 0x4f7ffffe, v4
	v_cvt_u32_f32_e32 v4, v4
	v_mul_lo_u32 v1, v3, v4
	v_mul_hi_u32 v1, v4, v1
	v_add_u32_e32 v1, v4, v1
	v_mul_hi_u32 v1, v5, v1
	v_mul_lo_u32 v3, v1, v2
	v_sub_u32_e32 v3, v5, v3
	v_add_u32_e32 v4, 1, v1
	v_cmp_ge_u32_e32 vcc, v3, v2
	s_nop 1
	v_cndmask_b32_e32 v1, v1, v4, vcc
	v_sub_u32_e32 v4, v3, v2
	v_cndmask_b32_e32 v3, v3, v4, vcc
	v_add_u32_e32 v4, 1, v1
	v_cmp_ge_u32_e32 vcc, v3, v2
	v_add_u32_e32 v3, 1, v5
	s_nop 0
	v_cndmask_b32_e32 v1, v1, v4, vcc
	v_mul_lo_u32 v4, v2, v1
	v_add_u32_e32 v2, v4, v2
	v_cmp_ne_u32_e32 vcc, v3, v2
	s_and_saveexec_b64 s[16:17], vcc
	s_xor_b64 s[16:17], exec, s[16:17]
	s_cbranch_execz .LBB0_1321
	s_waitcnt lgkmcnt(0)
	v_mov_b32_e32 v0, 0xe003500
	global_load_dword v0, v0, s[12:13] sc1
	s_add_u32 s36, s12, 0xe003500
	s_addc_u32 s37, s13, 0
	s_waitcnt vmcnt(0)
	v_cmp_eq_u32_e32 vcc, v0, v1
	s_and_saveexec_b64 s[18:19], vcc
	s_cbranch_execz .LBB0_1320
	s_add_u32 s20, s12, 0xe000200
	s_addc_u32 s21, s13, 0
	s_mov_b32 s26, 1
	s_mov_b64 s[38:39], 0
	v_mov_b32_e32 v0, 0
	s_branch .LBB0_1311

.LBB0_1338:
	s_or_b64 exec, exec, s[12:13]
	s_mov_b64 s[12:13], exec
	v_mbcnt_lo_u32_b32 v0, s12, 0
	v_mbcnt_hi_u32_b32 v0, s13, v0
	v_cmp_eq_u32_e32 vcc, 0, v0
	s_waitcnt vmcnt(0)
	buffer_inv sc1
	s_and_saveexec_b64 s[16:17], vcc
	s_cbranch_execz .LBB0_1340
	s_bcnt1_i32_b64 s12, s[12:13]
	v_mov_b32_e32 v0, 0x2000
	v_mov_b32_e32 v1, s12
.LBB0_1340:
	s_or_b64 exec, exec, s[16:17]
	s_waitcnt vmcnt(0)

.LBB0_1462:
	s_or_b64 exec, exec, s[18:19]
	v_cvt_f32_u32_e32 v4, v2
	s_waitcnt vmcnt(0)
	v_readfirstlane_b32 s16, v3
	v_sub_u32_e32 v3, 0, v2
	v_rcp_iflag_f32_e32 v4, v4
	v_add_u32_e32 v5, s16, v1
	v_mul_f32_e32 v4, 0x4f7ffffe, v4
	v_cvt_u32_f32_e32 v4, v4
	v_mul_lo_u32 v1, v3, v4
	v_mul_hi_u32 v1, v4, v1
	v_add_u32_e32 v1, v4, v1
	v_mul_hi_u32 v1, v5, v1
	v_mul_lo_u32 v3, v1, v2
	v_sub_u32_e32 v3, v5, v3
	v_add_u32_e32 v4, 1, v1
	v_cmp_ge_u32_e32 vcc, v3, v2
	s_nop 1
	v_cndmask_b32_e32 v1, v1, v4, vcc
	v_sub_u32_e32 v4, v3, v2
	v_cndmask_b32_e32 v3, v3, v4, vcc
	v_add_u32_e32 v4, 1, v1
	v_cmp_ge_u32_e32 vcc, v3, v2
	v_add_u32_e32 v3, 1, v5
	s_nop 0
	v_cndmask_b32_e32 v1, v1, v4, vcc
	v_mul_lo_u32 v4, v2, v1
	v_add_u32_e32 v2, v4, v2
	v_cmp_ne_u32_e32 vcc, v3, v2
	s_and_saveexec_b64 s[16:17], vcc
	s_xor_b64 s[16:17], exec, s[16:17]
	s_cbranch_execz .LBB0_1476
	s_waitcnt lgkmcnt(0)
	v_mov_b32_e32 v0, 0xe003500
	global_load_dword v0, v0, s[12:13] sc1
	s_add_u32 s22, s12, 0xe003500
	s_addc_u32 s23, s13, 0
	s_waitcnt vmcnt(0)
	v_cmp_eq_u32_e32 vcc, v0, v1
	s_and_saveexec_b64 s[18:19], vcc
	s_cbranch_execz .LBB0_1475
	s_add_u32 s20, s12, 0xe000200
	s_addc_u32 s21, s13, 0
	s_mov_b32 s26, 1
	s_mov_b64 s[36:37], 0
	v_mov_b32_e32 v0, 0
	s_branch .LBB0_1466

.LBB0_1493:
	s_or_b64 exec, exec, s[12:13]
	s_mov_b64 s[12:13], exec
	v_mbcnt_lo_u32_b32 v0, s12, 0
	v_mbcnt_hi_u32_b32 v0, s13, v0
	v_cmp_eq_u32_e32 vcc, 0, v0
	s_waitcnt vmcnt(0)
	buffer_inv sc1
	s_and_saveexec_b64 s[16:17], vcc
	s_cbranch_execz .LBB0_1495
	s_bcnt1_i32_b64 s12, s[12:13]
	v_mov_b32_e32 v0, 0x2000
	v_mov_b32_e32 v1, s12
.LBB0_1495:
	s_or_b64 exec, exec, s[16:17]
	s_waitcnt vmcnt(0)

.LBB0_1584:
	s_or_b64 exec, exec, s[12:13]
	s_mov_b64 s[12:13], exec
	v_mbcnt_lo_u32_b32 v0, s12, 0
	v_mbcnt_hi_u32_b32 v0, s13, v0
	v_cmp_eq_u32_e32 vcc, 0, v0
	s_waitcnt vmcnt(0)
	buffer_inv sc1
	s_and_saveexec_b64 s[16:17], vcc
	s_cbranch_execz .LBB0_1586
	s_bcnt1_i32_b64 s12, s[12:13]
	v_mov_b32_e32 v0, 0x2000
	v_mov_b32_e32 v1, s12
.LBB0_1586:
	s_or_b64 exec, exec, s[16:17]
	s_waitcnt vmcnt(0)

.LBB0_1675:
	s_or_b64 exec, exec, s[12:13]
	s_mov_b64 s[12:13], exec
	v_mbcnt_lo_u32_b32 v0, s12, 0
	v_mbcnt_hi_u32_b32 v0, s13, v0
	v_cmp_eq_u32_e32 vcc, 0, v0
	s_waitcnt vmcnt(0)
	buffer_inv sc1
	s_and_saveexec_b64 s[16:17], vcc
	s_cbranch_execz .LBB0_1677
	s_bcnt1_i32_b64 s12, s[12:13]
	v_mov_b32_e32 v0, 0x2000
	v_mov_b32_e32 v1, s12
.LBB0_1677:
	s_or_b64 exec, exec, s[16:17]
	s_waitcnt vmcnt(0)

.LBB0_1780:
	s_or_b64 exec, exec, s[16:17]
	v_cvt_f32_u32_e32 v4, v2
	s_waitcnt vmcnt(0)
	v_readfirstlane_b32 s14, v3
	v_sub_u32_e32 v3, 0, v2
	v_rcp_iflag_f32_e32 v4, v4
	v_add_u32_e32 v5, s14, v1
	v_mul_f32_e32 v4, 0x4f7ffffe, v4
	v_cvt_u32_f32_e32 v4, v4
	v_mul_lo_u32 v1, v3, v4
	v_mul_hi_u32 v1, v4, v1
	v_add_u32_e32 v1, v4, v1
	v_mul_hi_u32 v1, v5, v1
	v_mul_lo_u32 v3, v1, v2
	v_sub_u32_e32 v3, v5, v3
	v_add_u32_e32 v4, 1, v1
	v_cmp_ge_u32_e32 vcc, v3, v2
	s_nop 1
	v_cndmask_b32_e32 v1, v1, v4, vcc
	v_sub_u32_e32 v4, v3, v2
	v_cndmask_b32_e32 v3, v3, v4, vcc
	v_add_u32_e32 v4, 1, v1
	v_cmp_ge_u32_e32 vcc, v3, v2
	v_add_u32_e32 v3, 1, v5
	s_nop 0
	v_cndmask_b32_e32 v1, v1, v4, vcc
	v_mul_lo_u32 v4, v2, v1
	v_add_u32_e32 v2, v4, v2
	v_cmp_ne_u32_e32 vcc, v3, v2
	s_and_saveexec_b64 s[14:15], vcc
	s_xor_b64 s[14:15], exec, s[14:15]
	s_cbranch_execz .LBB0_1794
	s_waitcnt lgkmcnt(0)
	v_mov_b32_e32 v0, 0xe003500
	global_load_dword v0, v0, s[10:11] sc1
	s_add_u32 s20, s10, 0xe003500
	s_addc_u32 s21, s11, 0
	s_waitcnt vmcnt(0)
	v_cmp_eq_u32_e32 vcc, v0, v1
	s_and_saveexec_b64 s[16:17], vcc
	s_cbranch_execz .LBB0_1793
	s_add_u32 s18, s10, 0xe000200
	s_addc_u32 s19, s11, 0
	s_mov_b32 s26, 1
	s_mov_b64 s[22:23], 0
	v_mov_b32_e32 v0, 0
	s_branch .LBB0_1784

.LBB0_1811:
	s_or_b64 exec, exec, s[10:11]
	s_mov_b64 s[10:11], exec
	v_mbcnt_lo_u32_b32 v0, s10, 0
	v_mbcnt_hi_u32_b32 v0, s11, v0
	v_cmp_eq_u32_e32 vcc, 0, v0
	s_waitcnt vmcnt(0)
	buffer_inv sc1
	s_and_saveexec_b64 s[16:17], vcc
	s_cbranch_execz .LBB0_1813
	s_bcnt1_i32_b64 s10, s[10:11]
	v_mov_b32_e32 v0, 0x2000
	v_mov_b32_e32 v1, s10
.LBB0_1813:
	s_or_b64 exec, exec, s[16:17]
	s_waitcnt vmcnt(0)

.LBB0_1876:
	s_or_b64 exec, exec, s[20:21]
	v_cvt_f32_u32_e32 v4, v2
	s_waitcnt vmcnt(0)
	v_readfirstlane_b32 s18, v3
	v_sub_u32_e32 v3, 0, v2
	v_rcp_iflag_f32_e32 v4, v4
	v_add_u32_e32 v5, s18, v1
	v_mul_f32_e32 v4, 0x4f7ffffe, v4
	v_cvt_u32_f32_e32 v4, v4
	v_mul_lo_u32 v1, v3, v4
	v_mul_hi_u32 v1, v4, v1
	v_add_u32_e32 v1, v4, v1
	v_mul_hi_u32 v1, v5, v1
	v_mul_lo_u32 v3, v1, v2
	v_sub_u32_e32 v3, v5, v3
	v_add_u32_e32 v4, 1, v1
	v_cmp_ge_u32_e32 vcc, v3, v2
	s_nop 1
	v_cndmask_b32_e32 v1, v1, v4, vcc
	v_sub_u32_e32 v4, v3, v2
	v_cndmask_b32_e32 v3, v3, v4, vcc
	v_add_u32_e32 v4, 1, v1
	v_cmp_ge_u32_e32 vcc, v3, v2
	v_add_u32_e32 v3, 1, v5
	s_nop 0
	v_cndmask_b32_e32 v1, v1, v4, vcc
	v_mul_lo_u32 v4, v2, v1
	v_add_u32_e32 v2, v4, v2
	v_cmp_ne_u32_e32 vcc, v3, v2
	s_and_saveexec_b64 s[18:19], vcc
	s_xor_b64 s[18:19], exec, s[18:19]
	s_cbranch_execz .LBB0_1890
	s_waitcnt lgkmcnt(0)
	v_mov_b32_e32 v0, 0xe003500
	global_load_dword v0, v0, s[4:5] sc1
	s_add_u32 s34, s4, 0xe003500
	s_addc_u32 s35, s5, 0
	s_waitcnt vmcnt(0)
	v_cmp_eq_u32_e32 vcc, v0, v1
	s_and_saveexec_b64 s[20:21], vcc
	s_cbranch_execz .LBB0_1889
	s_add_u32 s22, s4, 0xe000200
	s_addc_u32 s23, s5, 0
	s_mov_b32 s25, 1
	s_mov_b64 s[36:37], 0
	v_mov_b32_e32 v0, 0
	s_branch .LBB0_1880

.LBB0_1907:
	s_or_b64 exec, exec, s[4:5]
	s_mov_b64 s[4:5], exec
	v_mbcnt_lo_u32_b32 v0, s4, 0
	v_mbcnt_hi_u32_b32 v0, s5, v0
	v_cmp_eq_u32_e32 vcc, 0, v0
	s_waitcnt vmcnt(0)
	buffer_inv sc1
	s_and_saveexec_b64 s[18:19], vcc
	s_cbranch_execz .LBB0_1909
	s_bcnt1_i32_b64 s4, s[4:5]
	v_mov_b32_e32 v0, 0x2000
	v_mov_b32_e32 v1, s4
.LBB0_1909:
	s_or_b64 exec, exec, s[18:19]
	s_waitcnt vmcnt(0)
